# v27: v26 + parameter loads hoisted in the remaining norm loops
# baseline (speedup 1.0000x reference)
; __device__ __forceinline__ unsigned pk_bf16(float lo, float hi) { f32x2 v; v.x = lo; v.y = hi; const bf16x2_t b = __builtin_convertvector(v, bf16x2_t); return __builtin_bit_cast(unsigned, b); }
; __device__ __forceinline__ void phase_norm(const Frame& F, const float* xl, const float* xc, const f16* x16, int l, int which, int r0, int nrows, int ci, int nc) {
;     ...
;     for (int row = gw; row < nrows; row += nw_) {
;         const bool lat = row < TL; const int mi = lat ? (row >> 12) : 8;
;         const float* sh = F.MOD + ((size_t)l * 9 + mi) * NMOD + (3 * which) * DM; const float* sc = sh + DM;
;         float v[2][8]; float ss = 0.f;
;         if (x16) {
;             const f16* xp = x16 + (size_t)row * DM;
; #pragma unroll
;             for (int j = 0; j < 2; ++j) { const f16x8 t = *(const f16x8*)(xp + j * 512 + F.lane * 8);
; #pragma unroll
;                 for (int e = 0; e < 8; ++e) v[j][e] = (float)t[e]; }
;         } else {
;             const float* xp = lat ? xl + (size_t)row * DM : xc + (size_t)(row - TL) * DM;
; #pragma unroll
;             for (int j = 0; j < 2; ++j) { const f32x4 a = *(const f32x4*)(xp + j * 512 + F.lane * 8), b = *(const f32x4*)(xp + j * 512 + F.lane * 8 + 4);
; #pragma unroll
;                 for (int e = 0; e < 4; ++e) { v[j][e] = a[e]; v[j][4 + e] = b[e]; } }
;         }
; #pragma unroll
;         for (int j = 0; j < 2; ++j)
; #pragma unroll
;             for (int e = 0; e < 8; ++e) ss += v[j][e] * v[j][e];
;         ss = wave_sum(ss);
;         const float rstd = rsqrtf(ss * (1.0f / DM) + 1e-6f);
; #pragma unroll
;         for (int j = 0; j < 2; ++j) { const int k = j * 512 + F.lane * 8;
;             float o[8];
; #pragma unroll
;             for (int q = 0; q < 2; ++q) { const f32x4 w = *(const f32x4*)(nw + k + 4 * q), s1 = *(const f32x4*)(sc + k + 4 * q), s0 = *(const f32x4*)(sh + k + 4 * q);
; #pragma unroll
;                 for (int e = 0; e < 4; ++e) o[4 * q + e] = v[j][4 * q + e] * rstd * w[e] * (1.0f + s1[e]) + s0[e]; }
;             u32x4 pk;
;             if (true) { pk.x = pk_bf16(o[0], o[1]); pk.y = pk_bf16(o[2], o[3]); pk.z = pk_bf16(o[4], o[5]); pk.w = pk_bf16(o[6], o[7]); }
;             else { pk.x = pk_f16(o[0], o[1]); pk.y = pk_f16(o[2], o[3]); pk.z = pk_f16(o[4], o[5]); pk.w = pk_f16(o[6], o[7]); }
;             *(u32x4*)(F.H16 + (size_t)row * DM + k) = pk; }
.LBB0_407:
	v_add_co_u32_e32 v16, vcc, s3, v6
	s_ashr_i32 s0, s4, 12
	s_nop 0
	v_addc_co_u32_e32 v17, vcc, -1, v7, vcc
	global_load_dwordx4 v[16:19], v[16:17], off
	v_add_co_u32_e32 v20, vcc, s5, v6
	s_ashr_i32 s1, s0, 31
	s_nop 0
	v_addc_co_u32_e32 v21, vcc, -1, v7, vcc
	global_load_dwordx4 v[20:23], v[20:21], off offset:-3072
	s_add_u32 s0, s12, s0
	s_addc_u32 s1, s7, s1
	s_mul_hi_u32 s2, s0, 0x9000
	s_mul_i32 s1, s1, 0x9000
	s_mul_i32 s0, s0, 0x9000
	s_add_i32 s2, s2, s1
	s_add_u32 s0, s18, s0
	s_addc_u32 s1, s19, s2
	s_add_u32 s10, s0, 0x3000
	s_addc_u32 s11, s1, 0
	s_add_u32 s16, s0, 0x4000
	s_addc_u32 s17, s1, 0
	global_load_dwordx4 v[24:27], v0, s[16:17] offset:16
	global_load_dwordx4 v[28:31], v[2:3], off offset:16
	global_load_dwordx4 v[32:35], v[2:3], off
	global_load_dwordx4 v[36:39], v0, s[10:11] offset:16
	global_load_dwordx4 v[40:43], v0, s[10:11]
	global_load_dwordx4 v[44:47], v0, s[16:17]
	global_load_dwordx4 v[100:103], v[4:5], off
	global_load_dwordx4 v[104:107], v14, s[16:17]
	global_load_dwordx4 v[108:111], v[4:5], off offset:16
	global_load_dwordx4 v[112:115], v14, s[16:17] offset:16
	global_load_dwordx4 v[116:119], v14, s[10:11]
	global_load_dwordx4 v[120:123], v14, s[10:11] offset:16
	s_add_i32 s4, s4, s6
	s_cmpk_gt_i32 s4, 0x7fff
	s_waitcnt vmcnt(13)
	v_cvt_f32_f16_e32 v52, v16
	v_cvt_f32_f16_sdwa v53, v16 dst_sel:DWORD dst_unused:UNUSED_PAD src0_sel:WORD_1
	v_cvt_f32_f16_e32 v48, v19
	v_cvt_f32_f16_sdwa v49, v19 dst_sel:DWORD dst_unused:UNUSED_PAD src0_sel:WORD_1
	v_cvt_f32_f16_e32 v50, v18
	v_cvt_f32_f16_sdwa v51, v18 dst_sel:DWORD dst_unused:UNUSED_PAD src0_sel:WORD_1
	v_cvt_f32_f16_e32 v18, v17
	v_cvt_f32_f16_sdwa v19, v17 dst_sel:DWORD dst_unused:UNUSED_PAD src0_sel:WORD_1
	v_pk_mul_f32 v[62:63], v[52:53], v[52:53]
	s_waitcnt vmcnt(12)
	v_cvt_f32_f16_e32 v54, v23
	v_cvt_f32_f16_sdwa v55, v23 dst_sel:DWORD dst_unused:UNUSED_PAD src0_sel:WORD_1
	v_cvt_f32_f16_e32 v56, v22
	v_cvt_f32_f16_sdwa v57, v22 dst_sel:DWORD dst_unused:UNUSED_PAD src0_sel:WORD_1
	v_pk_mul_f32 v[22:23], v[18:19], v[18:19]
	v_add_f32_e32 v15, v62, v63
	v_add_f32_e32 v15, v22, v15
	v_cvt_f32_f16_e32 v58, v21
	v_cvt_f32_f16_sdwa v59, v21 dst_sel:DWORD dst_unused:UNUSED_PAD src0_sel:WORD_1
	v_cvt_f32_f16_e32 v60, v20
	v_cvt_f32_f16_sdwa v61, v20 dst_sel:DWORD dst_unused:UNUSED_PAD src0_sel:WORD_1
	v_pk_mul_f32 v[20:21], v[50:51], v[50:51]
	v_add_f32_e32 v15, v23, v15
	v_add_f32_e32 v15, v20, v15
	v_pk_mul_f32 v[16:17], v[48:49], v[48:49]
	v_add_f32_e32 v15, v21, v15
	v_add_f32_e32 v15, v16, v15
	v_pk_mul_f32 v[70:71], v[60:61], v[60:61]
	v_add_f32_e32 v15, v17, v15
	v_add_f32_e32 v15, v70, v15
	v_pk_mul_f32 v[68:69], v[58:59], v[58:59]
	v_add_f32_e32 v15, v71, v15
	v_add_f32_e32 v15, v68, v15
	v_pk_mul_f32 v[66:67], v[56:57], v[56:57]
	v_add_f32_e32 v15, v69, v15
	v_add_f32_e32 v15, v66, v15
	v_pk_mul_f32 v[64:65], v[54:55], v[54:55]
	v_add_f32_e32 v15, v67, v15
	v_add_f32_e32 v15, v64, v15
	v_add_f32_e32 v15, v65, v15
	s_waitcnt lgkmcnt(0)
	v_mov_b32_e32 v16, v15
	s_nop 1
	v_permlane32_swap_b32_e32 v15, v16
	v_add_f32_e32 v15, v15, v16
	v_mov_b32_e32 v16, v15
	s_nop 1
	v_permlane16_swap_b32_e32 v15, v16
	v_add_f32_e32 v15, v15, v16
	s_nop 1
	v_add_f32_dpp v15, v15, v15 row_ror:8 row_mask:0xf bank_mask:0xf
	s_nop 1
	v_add_f32_dpp v15, v15, v15 row_ror:4 row_mask:0xf bank_mask:0xf
	s_nop 1
	v_add_f32_dpp v15, v15, v15 row_ror:2 row_mask:0xf bank_mask:0xf
	s_nop 1
	v_add_f32_dpp v15, v15, v15 row_ror:1 row_mask:0xf bank_mask:0xf
	s_waitcnt vmcnt(6)
	v_pk_add_f32 v[22:23], v[44:45], 1.0 op_sel_hi:[1,0]
	v_pk_add_f32 v[16:17], v[24:25], 1.0 op_sel_hi:[1,0]
	v_pk_add_f32 v[24:25], v[26:27], 1.0 op_sel_hi:[1,0]
	v_fmamk_f32 v15, v15, 0x3a800000, v235
	v_mul_f32_e32 v20, 0x4b800000, v15
	v_cmp_gt_f32_e32 vcc, s88, v15
	s_nop 1
	v_cndmask_b32_e32 v15, v15, v20, vcc
	v_rsq_f32_e32 v15, v15
	v_pk_add_f32 v[20:21], v[46:47], 1.0 op_sel_hi:[1,0]
	v_mul_f32_e32 v26, 0x45800000, v15
	v_cndmask_b32_e32 v44, v15, v26, vcc
	v_pk_mul_f32 v[26:27], v[44:45], v[52:53] op_sel_hi:[0,1]
	v_pk_mul_f32 v[18:19], v[44:45], v[18:19] op_sel_hi:[0,1]
	v_pk_mul_f32 v[46:47], v[44:45], v[50:51] op_sel_hi:[0,1]
	v_pk_mul_f32 v[48:49], v[44:45], v[48:49] op_sel_hi:[0,1]
	v_pk_mul_f32 v[26:27], v[32:33], v[26:27]
	v_pk_mul_f32 v[18:19], v[34:35], v[18:19]
	v_pk_mul_f32 v[28:29], v[28:29], v[46:47]
	v_pk_mul_f32 v[30:31], v[30:31], v[48:49]
	v_pk_fma_f32 v[22:23], v[22:23], v[26:27], v[40:41]
	v_pk_fma_f32 v[18:19], v[20:21], v[18:19], v[42:43]
	v_pk_fma_f32 v[20:21], v[16:17], v[28:29], v[36:37]
	v_pk_fma_f32 v[24:25], v[24:25], v[30:31], v[38:39]
	v_cvt_pk_bf16_f32 v16, v22, v23
	v_cvt_pk_bf16_f32 v17, v18, v19
	v_cvt_pk_bf16_f32 v18, v20, v21
	v_cvt_pk_bf16_f32 v19, v24, v25
	global_store_dwordx4 v[6:7], v[16:19], off
	v_pk_mul_f32 v[40:41], v[44:45], v[60:61] op_sel_hi:[0,1]
	v_pk_mul_f32 v[42:43], v[44:45], v[58:59] op_sel_hi:[0,1]
	v_pk_mul_f32 v[46:47], v[44:45], v[56:57] op_sel_hi:[0,1]
	v_pk_mul_f32 v[44:45], v[44:45], v[54:55] op_sel_hi:[0,1]
	s_waitcnt vmcnt(1)
	v_pk_mul_f32 v[100:101], v[100:101], v[40:41]
	v_pk_add_f32 v[104:105], v[104:105], 1.0 op_sel_hi:[1,0]
	v_pk_mul_f32 v[102:103], v[102:103], v[42:43]
	v_pk_add_f32 v[106:107], v[106:107], 1.0 op_sel_hi:[1,0]
	v_pk_mul_f32 v[108:109], v[108:109], v[46:47]
	v_pk_add_f32 v[112:113], v[112:113], 1.0 op_sel_hi:[1,0]
	v_pk_mul_f32 v[110:111], v[110:111], v[44:45]
	v_pk_add_f32 v[114:115], v[114:115], 1.0 op_sel_hi:[1,0]
	v_pk_fma_f32 v[100:101], v[104:105], v[100:101], v[116:117]
	v_pk_fma_f32 v[102:103], v[106:107], v[102:103], v[118:119]
	v_pk_fma_f32 v[104:105], v[112:113], v[108:109], v[120:121]
	v_pk_fma_f32 v[106:107], v[114:115], v[110:111], v[122:123]
	v_cvt_pk_bf16_f32 v100, v100, v101
	v_cvt_pk_bf16_f32 v101, v102, v103
	v_cvt_pk_bf16_f32 v102, v104, v105
	v_cvt_pk_bf16_f32 v103, v106, v107
	global_store_dwordx4 v[6:7], v[100:103], off offset:1024
	v_lshl_add_u64 v[6:7], v[6:7], 0, s[8:9]
	s_cbranch_scc0 .LBB0_407

; __device__ __forceinline__ unsigned pk_bf16(float lo, float hi) { f32x2 v; v.x = lo; v.y = hi; const bf16x2_t b = __builtin_convertvector(v, bf16x2_t); return __builtin_bit_cast(unsigned, b); }
; __device__ __forceinline__ void phase_norm(const Frame& F, const float* xl, const float* xc, const f16* x16, int l, int which, int r0, int nrows, int ci, int nc) {
;     ...
;     for (int row = gw; row < nrows; row += nw_) {
;         const bool lat = row < TL; const int mi = lat ? (row >> 12) : 8;
;         const float* sh = F.MOD + ((size_t)l * 9 + mi) * NMOD + (3 * which) * DM; const float* sc = sh + DM;
;         float v[2][8]; float ss = 0.f;
;         if (x16) {
;             const f16* xp = x16 + (size_t)row * DM;
; #pragma unroll
;             for (int j = 0; j < 2; ++j) { const f16x8 t = *(const f16x8*)(xp + j * 512 + F.lane * 8);
; #pragma unroll
;                 for (int e = 0; e < 8; ++e) v[j][e] = (float)t[e]; }
;         } else {
;             const float* xp = lat ? xl + (size_t)row * DM : xc + (size_t)(row - TL) * DM;
; #pragma unroll
;             for (int j = 0; j < 2; ++j) { const f32x4 a = *(const f32x4*)(xp + j * 512 + F.lane * 8), b = *(const f32x4*)(xp + j * 512 + F.lane * 8 + 4);
; #pragma unroll
;                 for (int e = 0; e < 4; ++e) { v[j][e] = a[e]; v[j][4 + e] = b[e]; } }
;         }
; #pragma unroll
;         for (int j = 0; j < 2; ++j)
; #pragma unroll
;             for (int e = 0; e < 8; ++e) ss += v[j][e] * v[j][e];
;         ss = wave_sum(ss);
;         const float rstd = rsqrtf(ss * (1.0f / DM) + 1e-6f);
; #pragma unroll
;         for (int j = 0; j < 2; ++j) { const int k = j * 512 + F.lane * 8;
;             float o[8];
; #pragma unroll
;             for (int q = 0; q < 2; ++q) { const f32x4 w = *(const f32x4*)(nw + k + 4 * q), s1 = *(const f32x4*)(sc + k + 4 * q), s0 = *(const f32x4*)(sh + k + 4 * q);
; #pragma unroll
;                 for (int e = 0; e < 4; ++e) o[4 * q + e] = v[j][4 * q + e] * rstd * w[e] * (1.0f + s1[e]) + s0[e]; }
;             u32x4 pk;
;             if (true) { pk.x = pk_bf16(o[0], o[1]); pk.y = pk_bf16(o[2], o[3]); pk.z = pk_bf16(o[4], o[5]); pk.w = pk_bf16(o[6], o[7]); }
;             else { pk.x = pk_f16(o[0], o[1]); pk.y = pk_f16(o[2], o[3]); pk.z = pk_f16(o[4], o[5]); pk.w = pk_f16(o[6], o[7]); }
;             *(u32x4*)(F.H16 + (size_t)row * DM + k) = pk; }
.LBB0_458:
	v_add_co_u32_e32 v18, vcc, s14, v6
	s_min_i32 s1, s4, 0x8000
	s_nop 0
	v_addc_co_u32_e32 v19, vcc, -1, v7, vcc
	global_load_dwordx4 v[18:21], v[18:19], off
	v_add_co_u32_e32 v22, vcc, s12, v6
	s_ashr_i32 s1, s1, 12
	s_nop 0
	v_addc_co_u32_e32 v23, vcc, -1, v7, vcc
	global_load_dwordx4 v[22:25], v[22:23], off offset:-3072
	s_ashr_i32 s2, s1, 31
	s_add_u32 s1, s13, s1
	s_addc_u32 s2, s5, s2
	s_mul_hi_u32 s3, s1, 0x9000
	s_mul_i32 s2, s2, 0x9000
	s_mul_i32 s1, s1, 0x9000
	s_add_i32 s3, s3, s2
	s_add_u32 s1, s6, s1
	s_addc_u32 s2, s7, s3
	s_add_u32 s8, s1, 0x3000
	s_addc_u32 s9, s2, 0
	s_add_u32 s10, s1, 0x4000
	s_addc_u32 s11, s2, 0
	global_load_dwordx4 v[26:29], v0, s[10:11] offset:16
	global_load_dwordx4 v[30:33], v[2:3], off offset:16
	global_load_dwordx4 v[34:37], v[2:3], off
	global_load_dwordx4 v[38:41], v0, s[8:9] offset:16
	global_load_dwordx4 v[42:45], v0, s[8:9]
	global_load_dwordx4 v[46:49], v0, s[10:11]
	global_load_dwordx4 v[100:103], v[4:5], off
	global_load_dwordx4 v[104:107], v16, s[10:11]
	global_load_dwordx4 v[108:111], v[4:5], off offset:16
	global_load_dwordx4 v[112:115], v16, s[10:11] offset:16
	global_load_dwordx4 v[116:119], v16, s[8:9]
	global_load_dwordx4 v[120:123], v16, s[8:9] offset:16
	s_add_i32 s4, s4, s0
	s_cmp_lt_i32 s4, 0x8800
	s_waitcnt vmcnt(13)
	v_cvt_f32_f16_e32 v54, v18
	v_cvt_f32_f16_sdwa v55, v18 dst_sel:DWORD dst_unused:UNUSED_PAD src0_sel:WORD_1
	v_cvt_f32_f16_e32 v50, v21
	v_cvt_f32_f16_sdwa v51, v21 dst_sel:DWORD dst_unused:UNUSED_PAD src0_sel:WORD_1
	v_cvt_f32_f16_e32 v52, v20
	v_cvt_f32_f16_sdwa v53, v20 dst_sel:DWORD dst_unused:UNUSED_PAD src0_sel:WORD_1
	v_cvt_f32_f16_e32 v20, v19
	v_cvt_f32_f16_sdwa v21, v19 dst_sel:DWORD dst_unused:UNUSED_PAD src0_sel:WORD_1
	v_pk_mul_f32 v[64:65], v[54:55], v[54:55]
	s_waitcnt vmcnt(12)
	v_cvt_f32_f16_e32 v56, v25
	v_cvt_f32_f16_sdwa v57, v25 dst_sel:DWORD dst_unused:UNUSED_PAD src0_sel:WORD_1
	v_cvt_f32_f16_e32 v58, v24
	v_cvt_f32_f16_sdwa v59, v24 dst_sel:DWORD dst_unused:UNUSED_PAD src0_sel:WORD_1
	v_pk_mul_f32 v[24:25], v[20:21], v[20:21]
	v_add_f32_e32 v17, v64, v65
	v_add_f32_e32 v17, v24, v17
	v_cvt_f32_f16_e32 v60, v23
	v_cvt_f32_f16_sdwa v61, v23 dst_sel:DWORD dst_unused:UNUSED_PAD src0_sel:WORD_1
	v_cvt_f32_f16_e32 v62, v22
	v_cvt_f32_f16_sdwa v63, v22 dst_sel:DWORD dst_unused:UNUSED_PAD src0_sel:WORD_1
	v_pk_mul_f32 v[22:23], v[52:53], v[52:53]
	v_add_f32_e32 v17, v25, v17
	v_add_f32_e32 v17, v22, v17
	v_pk_mul_f32 v[18:19], v[50:51], v[50:51]
	v_add_f32_e32 v17, v23, v17
	v_add_f32_e32 v17, v18, v17
	v_pk_mul_f32 v[72:73], v[62:63], v[62:63]
	v_add_f32_e32 v17, v19, v17
	v_add_f32_e32 v17, v72, v17
	v_pk_mul_f32 v[70:71], v[60:61], v[60:61]
	v_add_f32_e32 v17, v73, v17
	v_add_f32_e32 v17, v70, v17
	v_pk_mul_f32 v[68:69], v[58:59], v[58:59]
	v_add_f32_e32 v17, v71, v17
	v_add_f32_e32 v17, v68, v17
	v_pk_mul_f32 v[66:67], v[56:57], v[56:57]
	v_add_f32_e32 v17, v69, v17
	v_add_f32_e32 v17, v66, v17
	v_add_f32_e32 v17, v67, v17
	s_waitcnt lgkmcnt(0)
	v_mov_b32_e32 v18, v17
	s_nop 1
	v_permlane32_swap_b32_e32 v17, v18
	v_add_f32_e32 v17, v17, v18
	v_mov_b32_e32 v18, v17
	s_nop 1
	v_permlane16_swap_b32_e32 v17, v18
	v_add_f32_e32 v17, v17, v18
	s_nop 1
	v_add_f32_dpp v17, v17, v17 row_ror:8 row_mask:0xf bank_mask:0xf
	s_nop 1
	v_add_f32_dpp v17, v17, v17 row_ror:4 row_mask:0xf bank_mask:0xf
	s_nop 1
	v_add_f32_dpp v17, v17, v17 row_ror:2 row_mask:0xf bank_mask:0xf
	s_nop 1
	v_add_f32_dpp v17, v17, v17 row_ror:1 row_mask:0xf bank_mask:0xf
	s_waitcnt vmcnt(6)
	v_pk_add_f32 v[24:25], v[46:47], 1.0 op_sel_hi:[1,0]
	v_pk_add_f32 v[18:19], v[26:27], 1.0 op_sel_hi:[1,0]
	v_pk_add_f32 v[26:27], v[28:29], 1.0 op_sel_hi:[1,0]
	v_fmamk_f32 v17, v17, 0x3a800000, v235
	v_mul_f32_e32 v22, 0x4b800000, v17
	v_cmp_gt_f32_e32 vcc, s88, v17
	s_nop 1
	v_cndmask_b32_e32 v17, v17, v22, vcc
	v_rsq_f32_e32 v17, v17
	v_pk_add_f32 v[22:23], v[48:49], 1.0 op_sel_hi:[1,0]
	v_mul_f32_e32 v28, 0x45800000, v17
	v_cndmask_b32_e32 v46, v17, v28, vcc
	v_pk_mul_f32 v[28:29], v[46:47], v[54:55] op_sel_hi:[0,1]
	v_pk_mul_f32 v[20:21], v[46:47], v[20:21] op_sel_hi:[0,1]
	v_pk_mul_f32 v[48:49], v[46:47], v[52:53] op_sel_hi:[0,1]
	v_pk_mul_f32 v[50:51], v[46:47], v[50:51] op_sel_hi:[0,1]
	v_pk_mul_f32 v[28:29], v[34:35], v[28:29]
	v_pk_mul_f32 v[20:21], v[36:37], v[20:21]
	v_pk_mul_f32 v[30:31], v[30:31], v[48:49]
	v_pk_mul_f32 v[32:33], v[32:33], v[50:51]
	v_pk_fma_f32 v[24:25], v[24:25], v[28:29], v[42:43]
	v_pk_fma_f32 v[20:21], v[22:23], v[20:21], v[44:45]
	v_pk_fma_f32 v[22:23], v[18:19], v[30:31], v[38:39]
	v_pk_fma_f32 v[26:27], v[26:27], v[32:33], v[40:41]
	v_cvt_pk_bf16_f32 v18, v24, v25
	v_cvt_pk_bf16_f32 v19, v20, v21
	v_cvt_pk_bf16_f32 v20, v22, v23
	v_cvt_pk_bf16_f32 v21, v26, v27
	global_store_dwordx4 v[6:7], v[18:21], off
	v_pk_mul_f32 v[42:43], v[46:47], v[62:63] op_sel_hi:[0,1]
	v_pk_mul_f32 v[44:45], v[46:47], v[60:61] op_sel_hi:[0,1]
	v_pk_mul_f32 v[48:49], v[46:47], v[58:59] op_sel_hi:[0,1]
	v_pk_mul_f32 v[46:47], v[46:47], v[56:57] op_sel_hi:[0,1]
	s_waitcnt vmcnt(1)
	v_pk_mul_f32 v[100:101], v[100:101], v[42:43]
	v_pk_add_f32 v[104:105], v[104:105], 1.0 op_sel_hi:[1,0]
	v_pk_mul_f32 v[102:103], v[102:103], v[44:45]
	v_pk_add_f32 v[106:107], v[106:107], 1.0 op_sel_hi:[1,0]
	v_pk_mul_f32 v[108:109], v[108:109], v[48:49]
	v_pk_add_f32 v[112:113], v[112:113], 1.0 op_sel_hi:[1,0]
	v_pk_mul_f32 v[110:111], v[110:111], v[46:47]
	v_pk_add_f32 v[114:115], v[114:115], 1.0 op_sel_hi:[1,0]
	v_pk_fma_f32 v[100:101], v[104:105], v[100:101], v[116:117]
	v_pk_fma_f32 v[102:103], v[106:107], v[102:103], v[118:119]
	v_pk_fma_f32 v[104:105], v[112:113], v[108:109], v[120:121]
	v_pk_fma_f32 v[106:107], v[114:115], v[110:111], v[122:123]
	v_cvt_pk_bf16_f32 v100, v100, v101
	v_cvt_pk_bf16_f32 v101, v102, v103
	v_cvt_pk_bf16_f32 v102, v104, v105
	v_cvt_pk_bf16_f32 v103, v106, v107
	global_store_dwordx4 v[6:7], v[100:103], off offset:1024
	v_lshl_add_u64 v[6:7], v[6:7], 0, v[8:9]
	s_cbranch_scc1 .LBB0_458

; __device__ __forceinline__ unsigned pk_bf16(float lo, float hi) { f32x2 v; v.x = lo; v.y = hi; const bf16x2_t b = __builtin_convertvector(v, bf16x2_t); return __builtin_bit_cast(unsigned, b); }
; __device__ __forceinline__ void phase_norm(const Frame& F, const float* xl, const float* xc, const f16* x16, int l, int which, int r0, int nrows, int ci, int nc) {
;     ...
;     for (int row = gw; row < nrows; row += nw_) {
;         const bool lat = row < TL; const int mi = lat ? (row >> 12) : 8;
;         const float* sh = F.MOD + ((size_t)l * 9 + mi) * NMOD + (3 * which) * DM; const float* sc = sh + DM;
;         float v[2][8]; float ss = 0.f;
;         if (x16) {
;             const f16* xp = x16 + (size_t)row * DM;
; #pragma unroll
;             for (int j = 0; j < 2; ++j) { const f16x8 t = *(const f16x8*)(xp + j * 512 + F.lane * 8);
; #pragma unroll
;                 for (int e = 0; e < 8; ++e) v[j][e] = (float)t[e]; }
;         } else {
;             const float* xp = lat ? xl + (size_t)row * DM : xc + (size_t)(row - TL) * DM;
; #pragma unroll
;             for (int j = 0; j < 2; ++j) { const f32x4 a = *(const f32x4*)(xp + j * 512 + F.lane * 8), b = *(const f32x4*)(xp + j * 512 + F.lane * 8 + 4);
; #pragma unroll
;                 for (int e = 0; e < 4; ++e) { v[j][e] = a[e]; v[j][4 + e] = b[e]; } }
;         }
; #pragma unroll
;         for (int j = 0; j < 2; ++j)
; #pragma unroll
;             for (int e = 0; e < 8; ++e) ss += v[j][e] * v[j][e];
;         ss = wave_sum(ss);
;         const float rstd = rsqrtf(ss * (1.0f / DM) + 1e-6f);
; #pragma unroll
;         for (int j = 0; j < 2; ++j) { const int k = j * 512 + F.lane * 8;
;             float o[8];
; #pragma unroll
;             for (int q = 0; q < 2; ++q) { const f32x4 w = *(const f32x4*)(nw + k + 4 * q), s1 = *(const f32x4*)(sc + k + 4 * q), s0 = *(const f32x4*)(sh + k + 4 * q);
; #pragma unroll
;                 for (int e = 0; e < 4; ++e) o[4 * q + e] = v[j][4 * q + e] * rstd * w[e] * (1.0f + s1[e]) + s0[e]; }
;             u32x4 pk;
;             if (true) { pk.x = pk_bf16(o[0], o[1]); pk.y = pk_bf16(o[2], o[3]); pk.z = pk_bf16(o[4], o[5]); pk.w = pk_bf16(o[6], o[7]); }
;             else { pk.x = pk_f16(o[0], o[1]); pk.y = pk_f16(o[2], o[3]); pk.z = pk_f16(o[4], o[5]); pk.w = pk_f16(o[6], o[7]); }
;             *(u32x4*)(F.H16 + (size_t)row * DM + k) = pk; }
.LBB0_1200:
	v_add_co_u32_e32 v14, vcc, s20, v4
	s_ashr_i32 s2, s4, 12
	s_nop 0
	v_addc_co_u32_e32 v15, vcc, -1, v5, vcc
	global_load_dwordx4 v[14:17], v[14:15], off
	v_add_co_u32_e32 v18, vcc, s14, v4
	s_ashr_i32 s3, s2, 31
	s_nop 0
	v_addc_co_u32_e32 v19, vcc, -1, v5, vcc
	global_load_dwordx4 v[18:21], v[18:19], off offset:-3072
	s_add_u32 s2, s1, s2
	s_addc_u32 s3, s0, s3
	s_mul_hi_u32 s5, s2, 0x9000
	s_mul_i32 s3, s3, 0x9000
	s_mul_i32 s2, s2, 0x9000
	s_add_i32 s5, s5, s3
	s_add_u32 s16, s6, s2
	s_addc_u32 s17, s7, s5
	s_add_u32 s18, s16, 0x1000
	s_addc_u32 s19, s17, 0
	global_load_dwordx4 v[22:25], v0, s[18:19] offset:16
	global_load_dwordx4 v[26:29], v[2:3], off offset:16
	global_load_dwordx4 v[30:33], v[2:3], off
	global_load_dwordx4 v[34:37], v0, s[16:17] offset:16
	global_load_dwordx4 v[38:41], v0, s[16:17]
	global_load_dwordx4 v[42:45], v0, s[18:19]
	global_load_dwordx4 v[100:103], v[2:3], off offset:2048
	global_load_dwordx4 v[104:107], v12, s[18:19]
	global_load_dwordx4 v[108:111], v[2:3], off offset:2064
	global_load_dwordx4 v[112:115], v12, s[18:19] offset:16
	global_load_dwordx4 v[116:119], v0, s[16:17] offset:2048
	global_load_dwordx4 v[120:123], v0, s[16:17] offset:2064
	s_add_i32 s4, s4, s10
	s_cmp_lt_i32 s4, 0x8000
	s_waitcnt vmcnt(13)
	v_cvt_f32_f16_e32 v50, v14
	v_cvt_f32_f16_sdwa v51, v14 dst_sel:DWORD dst_unused:UNUSED_PAD src0_sel:WORD_1
	v_cvt_f32_f16_e32 v46, v17
	v_cvt_f32_f16_sdwa v47, v17 dst_sel:DWORD dst_unused:UNUSED_PAD src0_sel:WORD_1
	v_cvt_f32_f16_e32 v48, v16
	v_cvt_f32_f16_sdwa v49, v16 dst_sel:DWORD dst_unused:UNUSED_PAD src0_sel:WORD_1
	v_cvt_f32_f16_e32 v16, v15
	v_cvt_f32_f16_sdwa v17, v15 dst_sel:DWORD dst_unused:UNUSED_PAD src0_sel:WORD_1
	v_pk_mul_f32 v[60:61], v[50:51], v[50:51]
	s_waitcnt vmcnt(12)
	v_cvt_f32_f16_e32 v52, v21
	v_cvt_f32_f16_sdwa v53, v21 dst_sel:DWORD dst_unused:UNUSED_PAD src0_sel:WORD_1
	v_cvt_f32_f16_e32 v54, v20
	v_cvt_f32_f16_sdwa v55, v20 dst_sel:DWORD dst_unused:UNUSED_PAD src0_sel:WORD_1
	v_pk_mul_f32 v[20:21], v[16:17], v[16:17]
	v_add_f32_e32 v13, v60, v61
	v_add_f32_e32 v13, v20, v13
	v_cvt_f32_f16_e32 v56, v19
	v_cvt_f32_f16_sdwa v57, v19 dst_sel:DWORD dst_unused:UNUSED_PAD src0_sel:WORD_1
	v_cvt_f32_f16_e32 v58, v18
	v_cvt_f32_f16_sdwa v59, v18 dst_sel:DWORD dst_unused:UNUSED_PAD src0_sel:WORD_1
	v_pk_mul_f32 v[18:19], v[48:49], v[48:49]
	v_add_f32_e32 v13, v21, v13
	v_add_f32_e32 v13, v18, v13
	v_pk_mul_f32 v[14:15], v[46:47], v[46:47]
	v_add_f32_e32 v13, v19, v13
	v_add_f32_e32 v13, v14, v13
	v_pk_mul_f32 v[68:69], v[58:59], v[58:59]
	v_add_f32_e32 v13, v15, v13
	v_add_f32_e32 v13, v68, v13
	v_pk_mul_f32 v[66:67], v[56:57], v[56:57]
	v_add_f32_e32 v13, v69, v13
	v_add_f32_e32 v13, v66, v13
	v_pk_mul_f32 v[64:65], v[54:55], v[54:55]
	v_add_f32_e32 v13, v67, v13
	v_add_f32_e32 v13, v64, v13
	v_pk_mul_f32 v[62:63], v[52:53], v[52:53]
	v_add_f32_e32 v13, v65, v13
	v_add_f32_e32 v13, v62, v13
	v_add_f32_e32 v13, v63, v13
	s_waitcnt lgkmcnt(0)
	v_mov_b32_e32 v14, v13
	s_nop 1
	v_permlane32_swap_b32_e32 v13, v14
	v_add_f32_e32 v13, v13, v14
	v_mov_b32_e32 v14, v13
	s_nop 1
	v_permlane16_swap_b32_e32 v13, v14
	v_add_f32_e32 v13, v13, v14
	s_nop 1
	v_add_f32_dpp v13, v13, v13 row_ror:8 row_mask:0xf bank_mask:0xf
	s_nop 1
	v_add_f32_dpp v13, v13, v13 row_ror:4 row_mask:0xf bank_mask:0xf
	s_nop 1
	v_add_f32_dpp v13, v13, v13 row_ror:2 row_mask:0xf bank_mask:0xf
	s_nop 1
	v_add_f32_dpp v13, v13, v13 row_ror:1 row_mask:0xf bank_mask:0xf
	s_waitcnt vmcnt(6)
	v_pk_add_f32 v[20:21], v[42:43], 1.0 op_sel_hi:[1,0]
	v_pk_add_f32 v[14:15], v[22:23], 1.0 op_sel_hi:[1,0]
	v_pk_add_f32 v[22:23], v[24:25], 1.0 op_sel_hi:[1,0]
	v_fmamk_f32 v13, v13, 0x3a800000, v235
	v_mul_f32_e32 v18, 0x4b800000, v13
	v_cmp_gt_f32_e32 vcc, s88, v13
	s_nop 1
	v_cndmask_b32_e32 v13, v13, v18, vcc
	v_rsq_f32_e32 v13, v13
	v_pk_add_f32 v[18:19], v[44:45], 1.0 op_sel_hi:[1,0]
	v_mul_f32_e32 v24, 0x45800000, v13
	v_cndmask_b32_e32 v42, v13, v24, vcc
	v_pk_mul_f32 v[24:25], v[42:43], v[50:51] op_sel_hi:[0,1]
	v_pk_mul_f32 v[16:17], v[42:43], v[16:17] op_sel_hi:[0,1]
	v_pk_mul_f32 v[44:45], v[42:43], v[48:49] op_sel_hi:[0,1]
	v_pk_mul_f32 v[46:47], v[42:43], v[46:47] op_sel_hi:[0,1]
	v_pk_mul_f32 v[24:25], v[30:31], v[24:25]
	v_pk_mul_f32 v[16:17], v[32:33], v[16:17]
	v_pk_mul_f32 v[26:27], v[26:27], v[44:45]
	v_pk_mul_f32 v[28:29], v[28:29], v[46:47]
	v_pk_fma_f32 v[20:21], v[20:21], v[24:25], v[38:39]
	v_pk_fma_f32 v[16:17], v[18:19], v[16:17], v[40:41]
	v_pk_fma_f32 v[18:19], v[14:15], v[26:27], v[34:35]
	v_pk_fma_f32 v[22:23], v[22:23], v[28:29], v[36:37]
	v_cvt_pk_bf16_f32 v14, v20, v21
	v_cvt_pk_bf16_f32 v15, v16, v17
	v_cvt_pk_bf16_f32 v16, v18, v19
	v_cvt_pk_bf16_f32 v17, v22, v23
	global_store_dwordx4 v[4:5], v[14:17], off
	v_pk_mul_f32 v[38:39], v[42:43], v[58:59] op_sel_hi:[0,1]
	v_pk_mul_f32 v[40:41], v[42:43], v[56:57] op_sel_hi:[0,1]
	v_pk_mul_f32 v[44:45], v[42:43], v[54:55] op_sel_hi:[0,1]
	v_pk_mul_f32 v[42:43], v[42:43], v[52:53] op_sel_hi:[0,1]
	s_waitcnt vmcnt(1)
	v_pk_mul_f32 v[100:101], v[100:101], v[38:39]
	v_pk_add_f32 v[104:105], v[104:105], 1.0 op_sel_hi:[1,0]
	v_pk_mul_f32 v[102:103], v[102:103], v[40:41]
	v_pk_add_f32 v[106:107], v[106:107], 1.0 op_sel_hi:[1,0]
	v_pk_mul_f32 v[108:109], v[108:109], v[44:45]
	v_pk_add_f32 v[112:113], v[112:113], 1.0 op_sel_hi:[1,0]
	v_pk_mul_f32 v[110:111], v[110:111], v[42:43]
	v_pk_add_f32 v[114:115], v[114:115], 1.0 op_sel_hi:[1,0]
	v_pk_fma_f32 v[100:101], v[104:105], v[100:101], v[116:117]
	v_pk_fma_f32 v[102:103], v[106:107], v[102:103], v[118:119]
	v_pk_fma_f32 v[104:105], v[112:113], v[108:109], v[120:121]
	v_pk_fma_f32 v[106:107], v[114:115], v[110:111], v[122:123]
	v_cvt_pk_bf16_f32 v100, v100, v101
	v_cvt_pk_bf16_f32 v101, v102, v103
	v_cvt_pk_bf16_f32 v102, v104, v105
	v_cvt_pk_bf16_f32 v103, v106, v107
	global_store_dwordx4 v[4:5], v[100:103], off offset:1024
	v_lshl_add_u64 v[4:5], v[4:5], 0, s[8:9]
	s_cbranch_scc1 .LBB0_1200
